# v46 + hgrn_r3 final post-barrier output segment: the 8 state-fragment ds_read_b128 issued as a 6-deep rolling batch (v64-67, v214-233) with counted lgkmcnt 5/4/4/4/3/2/1/0 instead of read->lgkmcnt(0)-
# baseline (speedup 1.0000x reference)
; #define LAS __attribute__((address_space(3)))
; #define MFMA16(a, b, c) __builtin_amdgcn_mfma_f32_16x16x32_bf16((a), (b), (c), 0, 0, 0)
; __device__ __forceinline__ void hgrn_r3(const GAS bf16* proj, const GAS float* RU, const GAS float* RD, GAS bf16* y, int TOKG, const GAS float* ogain, unsigned char* lds, int tid, int lane, int wave, int bid, int G) {
;     ...
;             f32x4h acc[4];
; #pragma unroll
;             for (int t2 = 0; t2 < 4; ++t2) acc[t2] = (f32x4h){0.f, 0.f, 0.f, 0.f};
; #pragma unroll
;             for (int t2 = 0; t2 < 4; ++t2)
; #pragma unroll
;                 for (int ks = 0; ks < 4; ++ks) { const bf16x8 qf = *(const LAS bf16x8*)(L + H3_QH + (16 * t2 + fr) * HQS + (32 * ks + 8 * fq) * 2); acc[t2] = MFMA16(sf[ks], qf, acc[t2]); }
;             bf16x8 vf[2];
; #pragma unroll
;             for (int ks = 0; ks < 2; ++ks) vf[ks] = *(const LAS bf16x8*)(L + H3_VT + (16 * wave + fr) * HS + (32 * ks + 8 * fq) * 2);
; #pragma unroll
;             for (int nk = 0; nk < 8; ++nk) { const f32x4h dk = *(const LAS f32x4h*)(decl + 16 * nk + 4 * fq); Sm[nk] = Sm[nk] * dk;
; #pragma unroll
;                 for (int ks = 0; ks < 2; ++ks) { const bf16x8 kf = *(const LAS bf16x8*)(L + H3_KT + (16 * nk + fr) * HS + (32 * ks + 8 * fq) * 2); Sm[nk] = MFMA16(kf, vf[ks], Sm[nk]); } }
;             __syncthreads();
; #pragma unroll
;             for (int t2 = 0; t2 < 4; ++t2)
; #pragma unroll
;                 for (int ks = 0; ks < 2; ++ks) { const bf16x8 af = *(const LAS bf16x8*)(L + H3_AM + (16 * t2 + fr) * HS + (32 * ks + 8 * fq) * 2); acc[t2] = MFMA16(vf[ks], af, acc[t2]); }
; #pragma unroll
;             for (int t2 = 0; t2 < 4; ++t2) { float ss = acc[t2][0] * acc[t2][0] + acc[t2][1] * acc[t2][1] + acc[t2][2] * acc[t2][2] + acc[t2][3] * acc[t2][3];
;                 ss += __shfl_xor(ss, 16); ss += __shfl_xor(ss, 32); if (fq == 0) red[(16 * t2 + fr) * 8 + wave] = ss; }
.LBB0_392:
	s_nop 7
	v_cndmask_b32_e64 v52, v52, 0, s[30:31]
	v_cndmask_b32_e64 v53, 0, v53, s[34:35]
	v_cvt_pk_bf16_f32 v52, v52, v53
	v_cndmask_b32_e64 v53, v54, 0, s[36:37]
	v_cndmask_b32_e64 v54, v55, 0, s[38:39]
	v_cvt_pk_bf16_f32 v53, v53, v54
	ds_write_b64 v128, v[52:53]
	ds_read_b128 v[214:217], v129
	ds_read_b128 v[218:221], v129 offset:64
	ds_read_b128 v[222:225], v129 offset:128
	ds_read_b128 v[226:229], v129 offset:192
	ds_read_b128 v[230:233], v129 offset:4352
	ds_read_b128 v[64:67], v129 offset:4416
	s_waitcnt lgkmcnt(5)
	v_mfma_f32_16x16x32_bf16 v[52:55], v[48:51], v[214:217], 0
	ds_read_b128 v[214:217], v129 offset:4480
	s_waitcnt lgkmcnt(5)
	v_mfma_f32_16x16x32_bf16 v[52:55], v[44:47], v[218:221], v[52:55]
	ds_read_b128 v[218:221], v129 offset:4544
	s_waitcnt lgkmcnt(5)
	v_mfma_f32_16x16x32_bf16 v[52:55], v[40:43], v[222:225], v[52:55]
	ds_read_b128 v[222:225], v129 offset:8704
	s_waitcnt lgkmcnt(5)
	v_mfma_f32_16x16x32_bf16 v[52:55], v[36:39], v[226:229], v[52:55]
	ds_read_b128 v[226:229], v129 offset:8768
	s_waitcnt lgkmcnt(5)
	v_mfma_f32_16x16x32_bf16 v[56:59], v[48:51], v[230:233], 0
	ds_read_b128 v[230:233], v129 offset:8832
	s_waitcnt lgkmcnt(5)
	v_mfma_f32_16x16x32_bf16 v[56:59], v[44:47], v[64:67], v[56:59]
	ds_read_b128 v[64:67], v129 offset:8896
	s_waitcnt lgkmcnt(5)
	v_mfma_f32_16x16x32_bf16 v[56:59], v[40:43], v[214:217], v[56:59]
	ds_read_b128 v[214:217], v129 offset:13056
	s_waitcnt lgkmcnt(5)
	v_mfma_f32_16x16x32_bf16 v[56:59], v[36:39], v[218:221], v[56:59]
	ds_read_b128 v[218:221], v129 offset:13120
	s_waitcnt lgkmcnt(5)
	v_mfma_f32_16x16x32_bf16 v[60:63], v[48:51], v[222:225], 0
	ds_read_b128 v[222:225], v129 offset:13184
	s_waitcnt lgkmcnt(5)
	v_mfma_f32_16x16x32_bf16 v[60:63], v[44:47], v[226:229], v[60:63]
	ds_read_b128 v[226:229], v129 offset:13248
	s_waitcnt lgkmcnt(5)
	v_mfma_f32_16x16x32_bf16 v[60:63], v[40:43], v[230:233], v[60:63]
	s_waitcnt lgkmcnt(4)
	v_mfma_f32_16x16x32_bf16 v[60:63], v[36:39], v[64:67], v[60:63]
	s_waitcnt lgkmcnt(3)
	v_mfma_f32_16x16x32_bf16 v[48:51], v[48:51], v[214:217], 0
	s_waitcnt lgkmcnt(2)
	v_mfma_f32_16x16x32_bf16 v[44:47], v[44:47], v[218:221], v[48:51]
	s_waitcnt lgkmcnt(1)
	v_mfma_f32_16x16x32_bf16 v[40:43], v[40:43], v[222:225], v[44:47]
	s_waitcnt lgkmcnt(0)
	v_mfma_f32_16x16x32_bf16 v[40:43], v[36:39], v[226:229], v[40:43]
	s_nop 3
	ds_read_b128 v[44:47], v130 offset:52224
	ds_read_b128 v[36:39], v130 offset:52288
	ds_read_b128 v[48:51], v117
	ds_read_b128 v[214:217], v131
	ds_read_b128 v[218:221], v131 offset:64
	ds_read_b128 v[222:225], v117 offset:64
	ds_read_b128 v[226:229], v131 offset:2304
	ds_read_b128 v[230:233], v131 offset:2368
	s_waitcnt lgkmcnt(4)
	v_pk_mul_f32 v[22:23], v[22:23], v[50:51]
	v_pk_mul_f32 v[20:21], v[20:21], v[48:49]
	s_nop 1
	v_mfma_f32_16x16x32_bf16 v[20:23], v[214:217], v[44:47], v[20:23]
	s_waitcnt lgkmcnt(3)
	v_mfma_f32_16x16x32_bf16 v[20:23], v[218:221], v[36:39], v[20:23]
	ds_read_b128 v[48:51], v117 offset:128
	ds_read_b128 v[214:217], v131 offset:4608
	ds_read_b128 v[218:221], v131 offset:4672
	s_waitcnt lgkmcnt(4)
	v_pk_mul_f32 v[6:7], v[6:7], v[224:225]
	v_pk_mul_f32 v[4:5], v[4:5], v[222:223]
	s_nop 1
	v_mfma_f32_16x16x32_bf16 v[4:7], v[226:229], v[44:47], v[4:7]
	s_waitcnt lgkmcnt(3)
	v_mfma_f32_16x16x32_bf16 v[4:7], v[230:233], v[36:39], v[4:7]
	ds_read_b128 v[222:225], v117 offset:192
	ds_read_b128 v[226:229], v131 offset:6912
	ds_read_b128 v[230:233], v131 offset:6976
	s_waitcnt lgkmcnt(4)
	v_pk_mul_f32 v[18:19], v[18:19], v[50:51]
	v_pk_mul_f32 v[16:17], v[16:17], v[48:49]
	s_nop 1
	v_mfma_f32_16x16x32_bf16 v[16:19], v[214:217], v[44:47], v[16:19]
	s_waitcnt lgkmcnt(3)
	v_mfma_f32_16x16x32_bf16 v[16:19], v[218:221], v[36:39], v[16:19]
	ds_read_b128 v[48:51], v117 offset:256
	ds_read_b128 v[214:217], v131 offset:9216
	ds_read_b128 v[218:221], v131 offset:9280
	s_waitcnt lgkmcnt(4)
	v_pk_mul_f32 v[10:11], v[10:11], v[224:225]
	v_pk_mul_f32 v[8:9], v[8:9], v[222:223]
	s_nop 1
	v_mfma_f32_16x16x32_bf16 v[8:11], v[226:229], v[44:47], v[8:11]
	s_waitcnt lgkmcnt(3)
	v_mfma_f32_16x16x32_bf16 v[8:11], v[230:233], v[36:39], v[8:11]
	ds_read_b128 v[222:225], v117 offset:320
	ds_read_b128 v[226:229], v131 offset:11520
	ds_read_b128 v[230:233], v131 offset:11584
	s_waitcnt lgkmcnt(4)
	v_pk_mul_f32 v[26:27], v[26:27], v[50:51]
	v_pk_mul_f32 v[24:25], v[24:25], v[48:49]
	s_nop 1
	v_mfma_f32_16x16x32_bf16 v[24:27], v[214:217], v[44:47], v[24:27]
	s_waitcnt lgkmcnt(3)
	v_mfma_f32_16x16x32_bf16 v[24:27], v[218:221], v[36:39], v[24:27]
	ds_read_b128 v[48:51], v117 offset:384
	ds_read_b128 v[214:217], v131 offset:13824
	ds_read_b128 v[218:221], v131 offset:13888
	s_waitcnt lgkmcnt(4)
	v_pk_mul_f32 v[14:15], v[14:15], v[224:225]
	v_pk_mul_f32 v[12:13], v[12:13], v[222:223]
	s_nop 1
	v_mfma_f32_16x16x32_bf16 v[12:15], v[226:229], v[44:47], v[12:15]
	s_waitcnt lgkmcnt(3)
	v_mfma_f32_16x16x32_bf16 v[12:15], v[230:233], v[36:39], v[12:15]
	ds_read_b128 v[222:225], v117 offset:448
	ds_read_b128 v[226:229], v131 offset:16128
	ds_read_b128 v[230:233], v131 offset:16192
	s_waitcnt lgkmcnt(4)
	v_pk_mul_f32 v[30:31], v[30:31], v[50:51]
	v_pk_mul_f32 v[28:29], v[28:29], v[48:49]
	s_nop 1
	v_mfma_f32_16x16x32_bf16 v[28:31], v[214:217], v[44:47], v[28:31]
	s_waitcnt lgkmcnt(3)
	v_mfma_f32_16x16x32_bf16 v[28:31], v[218:221], v[36:39], v[28:31]
	s_waitcnt lgkmcnt(1)
	v_pk_mul_f32 v[34:35], v[34:35], v[224:225]
	v_pk_mul_f32 v[32:33], v[32:33], v[222:223]
	s_nop 1
	v_mfma_f32_16x16x32_bf16 v[32:35], v[226:229], v[44:47], v[32:35]
	s_waitcnt lgkmcnt(0)
	s_barrier
	v_mfma_f32_16x16x32_bf16 v[32:35], v[230:233], v[36:39], v[32:35]
	ds_read_b128 v[64:67], v132
	ds_read_b128 v[214:217], v132 offset:64
	ds_read_b128 v[218:221], v132 offset:2304
	ds_read_b128 v[222:225], v132 offset:2368
	ds_read_b128 v[226:229], v132 offset:4608
	ds_read_b128 v[230:233], v132 offset:4672
	s_waitcnt lgkmcnt(5)
	v_mfma_f32_16x16x32_bf16 v[48:51], v[44:47], v[64:67], v[52:55]
	s_waitcnt lgkmcnt(4)
	v_mfma_f32_16x16x32_bf16 v[64:67], v[36:39], v[214:217], v[48:51]
	ds_read_b128 v[214:217], v132 offset:6912
	s_waitcnt lgkmcnt(4)
	v_mfma_f32_16x16x32_bf16 v[48:51], v[44:47], v[218:221], v[56:59]
	ds_read_b128 v[218:221], v132 offset:6976
	s_waitcnt lgkmcnt(4)
	v_mfma_f32_16x16x32_bf16 v[52:55], v[36:39], v[222:225], v[48:51]
	s_waitcnt lgkmcnt(3)
	v_mfma_f32_16x16x32_bf16 v[48:51], v[44:47], v[226:229], v[60:63]
	s_waitcnt lgkmcnt(2)
	v_mfma_f32_16x16x32_bf16 v[48:51], v[36:39], v[230:233], v[48:51]
	s_waitcnt lgkmcnt(1)
	v_mfma_f32_16x16x32_bf16 v[40:43], v[44:47], v[214:217], v[40:43]
	s_waitcnt lgkmcnt(0)
	v_mfma_f32_16x16x32_bf16 v[36:39], v[36:39], v[218:221], v[40:43]
	s_nop 4
	v_mul_f32_e32 v40, v65, v65
	v_fmac_f32_e32 v40, v64, v64
	v_fmac_f32_e32 v40, v66, v66
	v_fmac_f32_e32 v40, v67, v67
	ds_bpermute_b32 v41, v118, v40
	s_waitcnt lgkmcnt(0)
	v_add_f32_e32 v40, v40, v41
	ds_bpermute_b32 v41, v119, v40
	s_and_saveexec_b64 vcc, s[4:5]
	s_cbranch_execz .LBB0_394
	s_waitcnt lgkmcnt(0)
	v_add_f32_e32 v40, v40, v41
	ds_write_b32 v135, v40
